# GEMM accumulator zero-init with 64 v_mov_b64 instead of 128 v_mov_b32 per tile (INPROJ, GU, QKV)
# speedup vs baseline: 1.0044x; 1.0044x over previous
; template <int EPI>
; __device__ __forceinline__ void gemm_acc_init(KP P, f32x4 (&acc)[2][2][4][2], int brow, int bcol, int wr, int wc, int fr_, int fq_, const float* sRu) {
;     ...
; #pragma unroll
;     for (int ai = 0; ai < 2; ++ai)
; #pragma unroll
;       for (int bj = 0; bj < 2; ++bj)
; #pragma unroll
;         for (int m = 0; m < 4; ++m)
; #pragma unroll
;           for (int n = 0; n < 2; ++n) acc[ai][bj][m][n] = f32x4{0.f, 0.f, 0.f, 0.f};
.LBB0_97:
	s_ashr_i32 s27, s26, 31
	s_lshl_b64 s[28:29], s[26:27], 19
	s_add_u32 s9, s47, s28
	s_addc_u32 s27, s48, s29
	s_ashr_i32 s25, s24, 31
	s_lshl_b64 s[30:31], s[24:25], 19
	s_add_u32 s25, s49, s30
	s_addc_u32 s34, s50, s31
	s_add_u32 s35, s18, s6
	s_addc_u32 s36, s19, s7
	s_add_u32 s37, s95, s4
	v_mov_b64_e32 v[2:3], 0
	v_lshl_add_u64 v[130:131], v[138:139], 0, s[6:7]
	v_lshl_add_u64 v[132:133], v[140:141], 0, s[6:7]
	s_addc_u32 s38, s88, s5
	s_mov_b32 s39, -2
	s_mov_b64 s[4:5], 0
	v_mov_b64_e32 v[4:5], 0
	v_mov_b64_e32 v[6:7], 0
	v_mov_b64_e32 v[8:9], 0
	v_mov_b64_e32 v[10:11], 0
	v_mov_b64_e32 v[12:13], 0
	v_mov_b64_e32 v[14:15], 0
	v_mov_b64_e32 v[16:17], 0
	v_mov_b64_e32 v[18:19], 0
	v_mov_b64_e32 v[20:21], 0
	v_mov_b64_e32 v[22:23], 0
	v_mov_b64_e32 v[24:25], 0
	v_mov_b64_e32 v[26:27], 0
	v_mov_b64_e32 v[28:29], 0
	v_mov_b64_e32 v[30:31], 0
	v_mov_b64_e32 v[32:33], 0
	v_mov_b64_e32 v[66:67], 0
	v_mov_b64_e32 v[68:69], 0
	v_mov_b64_e32 v[70:71], 0
	v_mov_b64_e32 v[72:73], 0
	v_mov_b64_e32 v[74:75], 0
	v_mov_b64_e32 v[76:77], 0
	v_mov_b64_e32 v[78:79], 0
	v_mov_b64_e32 v[80:81], 0
	v_mov_b64_e32 v[82:83], 0
	v_mov_b64_e32 v[84:85], 0
	v_mov_b64_e32 v[86:87], 0
	v_mov_b64_e32 v[88:89], 0
	v_mov_b64_e32 v[90:91], 0
	v_mov_b64_e32 v[92:93], 0
	v_mov_b64_e32 v[94:95], 0
	v_mov_b64_e32 v[96:97], 0
	v_mov_b64_e32 v[34:35], 0
	v_mov_b64_e32 v[36:37], 0
	v_mov_b64_e32 v[38:39], 0
	v_mov_b64_e32 v[40:41], 0
	v_mov_b64_e32 v[42:43], 0
	v_mov_b64_e32 v[44:45], 0
	v_mov_b64_e32 v[46:47], 0
	v_mov_b64_e32 v[48:49], 0
	v_mov_b64_e32 v[50:51], 0
	v_mov_b64_e32 v[52:53], 0
	v_mov_b64_e32 v[54:55], 0
	v_mov_b64_e32 v[56:57], 0
	v_mov_b64_e32 v[58:59], 0
	v_mov_b64_e32 v[60:61], 0
	v_mov_b64_e32 v[62:63], 0
	v_mov_b64_e32 v[64:65], 0
	v_mov_b64_e32 v[98:99], 0
	v_mov_b64_e32 v[100:101], 0
	v_mov_b64_e32 v[102:103], 0
	v_mov_b64_e32 v[104:105], 0
	v_mov_b64_e32 v[106:107], 0
	v_mov_b64_e32 v[108:109], 0
	v_mov_b64_e32 v[110:111], 0
	v_mov_b64_e32 v[112:113], 0
	v_mov_b64_e32 v[114:115], 0
	v_mov_b64_e32 v[116:117], 0
	v_mov_b64_e32 v[118:119], 0
	v_mov_b64_e32 v[120:121], 0
	v_mov_b64_e32 v[122:123], 0
	v_mov_b64_e32 v[124:125], 0
	v_mov_b64_e32 v[126:127], 0
	v_mov_b64_e32 v[128:129], 0

; template <int EPI>
; __device__ __forceinline__ void gemm_acc_init(KP P, f32x4 (&acc)[2][2][4][2], int brow, int bcol, int wr, int wc, int fr_, int fq_, const float* sRu) {
;     ...
; #pragma unroll
;     for (int ai = 0; ai < 2; ++ai)
; #pragma unroll
;       for (int bj = 0; bj < 2; ++bj)
; #pragma unroll
;         for (int m = 0; m < 4; ++m)
; #pragma unroll
;           for (int n = 0; n < 2; ++n) acc[ai][bj][m][n] = f32x4{0.f, 0.f, 0.f, 0.f};
.LBB0_263:
	s_ashr_i32 s15, s14, 31
	s_lshl_b64 s[16:17], s[14:15], 19
	s_add_u32 s15, s29, s16
	s_addc_u32 s71, s30, s17
	s_ashr_i32 s11, s10, 31
	s_lshl_b64 s[18:19], s[10:11], 19
	s_add_u32 s11, s31, s18
	s_addc_u32 s74, s34, s19
	s_add_u32 s75, s4, s24
	s_addc_u32 s76, s5, s25
	s_add_u32 s77, s67, s22
	v_mov_b64_e32 v[2:3], 0
	v_lshl_add_u64 v[138:139], v[134:135], 0, s[24:25]
	v_lshl_add_u64 v[140:141], v[136:137], 0, s[24:25]
	s_addc_u32 s78, s70, s23
	s_mov_b32 s79, -2
	s_mov_b64 s[22:23], 0
	v_mov_b64_e32 v[4:5], 0
	v_mov_b64_e32 v[6:7], 0
	v_mov_b64_e32 v[8:9], 0
	v_mov_b64_e32 v[18:19], 0
	v_mov_b64_e32 v[20:21], 0
	v_mov_b64_e32 v[22:23], 0
	v_mov_b64_e32 v[24:25], 0
	v_mov_b64_e32 v[34:35], 0
	v_mov_b64_e32 v[36:37], 0
	v_mov_b64_e32 v[38:39], 0
	v_mov_b64_e32 v[40:41], 0
	v_mov_b64_e32 v[50:51], 0
	v_mov_b64_e32 v[52:53], 0
	v_mov_b64_e32 v[54:55], 0
	v_mov_b64_e32 v[56:57], 0
	v_mov_b64_e32 v[10:11], 0
	v_mov_b64_e32 v[12:13], 0
	v_mov_b64_e32 v[14:15], 0
	v_mov_b64_e32 v[16:17], 0
	v_mov_b64_e32 v[26:27], 0
	v_mov_b64_e32 v[28:29], 0
	v_mov_b64_e32 v[30:31], 0
	v_mov_b64_e32 v[32:33], 0
	v_mov_b64_e32 v[42:43], 0
	v_mov_b64_e32 v[44:45], 0
	v_mov_b64_e32 v[46:47], 0
	v_mov_b64_e32 v[48:49], 0
	v_mov_b64_e32 v[58:59], 0
	v_mov_b64_e32 v[60:61], 0
	v_mov_b64_e32 v[62:63], 0
	v_mov_b64_e32 v[64:65], 0
	v_mov_b64_e32 v[66:67], 0
	v_mov_b64_e32 v[68:69], 0
	v_mov_b64_e32 v[70:71], 0
	v_mov_b64_e32 v[72:73], 0
	v_mov_b64_e32 v[82:83], 0
	v_mov_b64_e32 v[84:85], 0
	v_mov_b64_e32 v[86:87], 0
	v_mov_b64_e32 v[88:89], 0
	v_mov_b64_e32 v[98:99], 0
	v_mov_b64_e32 v[100:101], 0
	v_mov_b64_e32 v[102:103], 0
	v_mov_b64_e32 v[104:105], 0
	v_mov_b64_e32 v[114:115], 0
	v_mov_b64_e32 v[116:117], 0
	v_mov_b64_e32 v[118:119], 0
	v_mov_b64_e32 v[120:121], 0
	v_mov_b64_e32 v[74:75], 0
	v_mov_b64_e32 v[76:77], 0
	v_mov_b64_e32 v[78:79], 0
	v_mov_b64_e32 v[80:81], 0
	v_mov_b64_e32 v[90:91], 0
	v_mov_b64_e32 v[92:93], 0
	v_mov_b64_e32 v[94:95], 0
	v_mov_b64_e32 v[96:97], 0
	v_mov_b64_e32 v[106:107], 0
	v_mov_b64_e32 v[108:109], 0
	v_mov_b64_e32 v[110:111], 0
	v_mov_b64_e32 v[112:113], 0
	v_mov_b64_e32 v[122:123], 0
	v_mov_b64_e32 v[124:125], 0
	v_mov_b64_e32 v[126:127], 0
	v_mov_b64_e32 v[128:129], 0

; template <int EPI>
; __device__ __forceinline__ void gemm_acc_init(KP P, f32x4 (&acc)[2][2][4][2], int brow, int bcol, int wr, int wc, int fr_, int fq_, const float* sRu) {
;     ...
; #pragma unroll
;     for (int ai = 0; ai < 2; ++ai)
; #pragma unroll
;       for (int bj = 0; bj < 2; ++bj)
; #pragma unroll
;         for (int m = 0; m < 4; ++m)
; #pragma unroll
;           for (int n = 0; n < 2; ++n) acc[ai][bj][m][n] = f32x4{0.f, 0.f, 0.f, 0.f};
.LBB0_455:
	s_ashr_i32 s9, s8, 31
	s_lshl_b64 s[10:11], s[8:9], 19
	s_add_u32 s2, s23, s10
	s_addc_u32 s9, s24, s11
	s_ashr_i32 s15, s14, 31
	s_lshl_b64 s[12:13], s[14:15], 19
	s_add_u32 s15, s6, s12
	s_addc_u32 s52, s7, s13
	s_add_u32 s62, s6, s18
	s_addc_u32 s67, s7, s19
	s_add_u32 s70, s49, s4
	v_mov_b64_e32 v[2:3], 0
	s_addc_u32 s71, s50, s5
	s_mov_b32 s74, -2
	s_mov_b64 s[4:5], 0
	v_mov_b64_e32 v[4:5], 0
	v_mov_b64_e32 v[6:7], 0
	v_mov_b64_e32 v[8:9], 0
	v_mov_b64_e32 v[18:19], 0
	v_mov_b64_e32 v[20:21], 0
	v_mov_b64_e32 v[22:23], 0
	v_mov_b64_e32 v[24:25], 0
	v_mov_b64_e32 v[34:35], 0
	v_mov_b64_e32 v[36:37], 0
	v_mov_b64_e32 v[38:39], 0
	v_mov_b64_e32 v[40:41], 0
	v_mov_b64_e32 v[50:51], 0
	v_mov_b64_e32 v[52:53], 0
	v_mov_b64_e32 v[54:55], 0
	v_mov_b64_e32 v[56:57], 0
	v_mov_b64_e32 v[10:11], 0
	v_mov_b64_e32 v[12:13], 0
	v_mov_b64_e32 v[14:15], 0
	v_mov_b64_e32 v[16:17], 0
	v_mov_b64_e32 v[26:27], 0
	v_mov_b64_e32 v[28:29], 0
	v_mov_b64_e32 v[30:31], 0
	v_mov_b64_e32 v[32:33], 0
	v_mov_b64_e32 v[42:43], 0
	v_mov_b64_e32 v[44:45], 0
	v_mov_b64_e32 v[46:47], 0
	v_mov_b64_e32 v[48:49], 0
	v_mov_b64_e32 v[58:59], 0
	v_mov_b64_e32 v[60:61], 0
	v_mov_b64_e32 v[62:63], 0
	v_mov_b64_e32 v[64:65], 0
	v_mov_b64_e32 v[66:67], 0
	v_mov_b64_e32 v[68:69], 0
	v_mov_b64_e32 v[70:71], 0
	v_mov_b64_e32 v[72:73], 0
	v_mov_b64_e32 v[82:83], 0
	v_mov_b64_e32 v[84:85], 0
	v_mov_b64_e32 v[86:87], 0
	v_mov_b64_e32 v[88:89], 0
	v_mov_b64_e32 v[98:99], 0
	v_mov_b64_e32 v[100:101], 0
	v_mov_b64_e32 v[102:103], 0
	v_mov_b64_e32 v[104:105], 0
	v_mov_b64_e32 v[114:115], 0
	v_mov_b64_e32 v[116:117], 0
	v_mov_b64_e32 v[118:119], 0
	v_mov_b64_e32 v[120:121], 0
	v_mov_b64_e32 v[74:75], 0
	v_mov_b64_e32 v[76:77], 0
	v_mov_b64_e32 v[78:79], 0
	v_mov_b64_e32 v[80:81], 0
	v_mov_b64_e32 v[90:91], 0
	v_mov_b64_e32 v[92:93], 0
	v_mov_b64_e32 v[94:95], 0
	v_mov_b64_e32 v[96:97], 0
	v_mov_b64_e32 v[106:107], 0
	v_mov_b64_e32 v[108:109], 0
	v_mov_b64_e32 v[110:111], 0
	v_mov_b64_e32 v[112:113], 0
	v_mov_b64_e32 v[122:123], 0
	v_mov_b64_e32 v[124:125], 0
	v_mov_b64_e32 v[126:127], 0
	v_mov_b64_e32 v[128:129], 0
	v_lshl_add_u64 v[130:131], v[154:155], 0, s[18:19]
	v_lshl_add_u64 v[132:133], v[156:157], 0, s[18:19]
